# m2 + FoX loop: K/decay-bias LDS fragment reads issued before the next tile's global loads (loads moved behind them with renamed address temps; stub for inactive waves)
# baseline (speedup 1.0000x reference)
; template <int DK, int MODE, bool OUTF32> ...
;     ...
;         if (t + 1 < t_hi) A_ISSUE(t + 1);
;         bool act;
;         if (MODE == 0) act = (64 * t + 32 * kh) <= (qw0 + 31);
;         else if (MODE == 1) act = (t <= cw) && (t >= cw - 8);
;         else act = (t <= cw);
;         if (act) {
.Lfx_inact:
	s_or_b64 exec, exec, s[46:47]
	v_add_co_u32_e32 v246, vcc, 0xfff80000, v162
	global_load_dwordx4 v[140:143], v[166:167], off
	global_load_dwordx4 v[136:139], v[164:165], off
	v_addc_co_u32_e32 v247, vcc, -1, v163, vcc
	global_load_dwordx4 v[148:151], v[246:247], off
	global_load_dwordx4 v[144:147], v[162:163], off
	s_and_saveexec_b64 s[12:13], s[40:41]
	s_cbranch_execz .Lfx_nooffs_b
	global_load_dwordx4 v[132:135], v[160:161], off
	v_add_u32_e32 v250, s14, v185
	v_ashrrev_i32_e32 v250, 5, v250
	v_lshl_add_u32 v250, v250, 2, 0
	v_add_u32_e32 v250, 0x15200, v250
	ds_read_b32 v158, v250
.Lfx_nooffs_b:
	s_or_b64 exec, exec, s[12:13]
	s_branch .LBB0_288

; template <int DK, int MODE, bool OUTF32> ...
;     ...
;     for (int t = t_lo; t < t_hi; ++t) {
;         const int cur = (t - t_lo) & 1;
;         if (t + 1 < t_hi) A_ISSUE(t + 1);
;         bool act;
;         if (MODE == 0) act = (64 * t + 32 * kh) <= (qw0 + 31);
;         else if (MODE == 1) act = (t <= cw) && (t >= cw - 8);
;         else act = (t <= cw);
;         if (act) {
;             f32x16 p;
; #pragma unroll
;             for (int r = 0; r < 16; ++r) p[r] = 0.f;
;             const unsigned char* kb = a_lds + cur * KBUF + (32 * kh + c) * KP + hi * 16;
;             constexpr bool HOISTK = true;
;             bf16x8 kf[NKS];
;             if (HOISTK) {
; #pragma unroll
;                 for (int s = 0; s < NKS; ++s) kf[s] = *(const bf16x8*)(kb + s * 32);
;             }
;             const unsigned char* vb = a_lds + OFF_V + cur * VBUF + c * VP + (32 * kh + 4 * hi) * 2;
;             bf16x8 vf[8];
;     ...
;             constexpr bool HOISTV = (DK == 128) && (MODE == 2 || MODE == 1);
;             if (HOISTV) A_VREADS(0, 3);
;             if (HOISTK) __builtin_amdgcn_sched_barrier(0);
; #pragma unroll
;             for (int s = 0; s < NKS; ++s) p = __builtin_amdgcn_mfma_f32_32x32x16_bf16(HOISTK ? kf[s] : *(const bf16x8*)(kb + s * 32), qf[s], p, 0, 0, 0);
;             if (HOISTV) { A_VREADS(3, 4); __builtin_amdgcn_sched_barrier(0); }
;             if (MODE == 0) {
;                 const float* ckp = (const float*)(a_lds + OFF_CK + cur * 256) + 32 * kh + 4 * hi;
; #pragma unroll
;                 for (int g = 0; g < 4; ++g) {
;                     const float4 ck = *(const float4*)(ckp + 8 * g);
;                     p[4 * g + 0] = fmaf(p[4 * g + 0], sc2, cq - ck.x); p[4 * g + 1] = fmaf(p[4 * g + 1], sc2, cq - ck.y);
;                     p[4 * g + 2] = fmaf(p[4 * g + 2], sc2, cq - ck.z); p[4 * g + 3] = fmaf(p[4 * g + 3], sc2, cq - ck.w);
;                 }
;                 if (64 * t + 32 * kh + 31 > qw0) {
;                     const int kbase = 64 * t + 32 * kh + 4 * hi;
; #pragma unroll
;                     for (int r = 0; r < 16; ++r) if (kbase + (r & 3) + 8 * (r >> 2) > qrow) p[r] = NEGINF;
.LBB0_280:
	v_add_u32_e32 v186, s14, v181
	s_and_b32 s16, s15, 1
	v_cmp_le_i32_e32 vcc, v186, v182
	s_and_saveexec_b64 s[46:47], vcc
	s_cbranch_execz .Lfx_inact
	s_mul_i32 s17, s16, 0x4400
	v_add_u32_e32 v88, s17, v177
	v_lshl_add_u32 v187, s16, 8, v173
	ds_read_b128 v[84:87], v88
	ds_read_b128 v[188:191], v88 offset:32
	ds_read_b128 v[208:211], v88 offset:64
	ds_read_b128 v[212:215], v88 offset:96
	ds_read_b128 v[216:219], v88 offset:128
	ds_read_b128 v[220:223], v88 offset:160
	ds_read_b128 v[224:227], v88 offset:192
	ds_read_b128 v[228:231], v88 offset:224
	ds_read_b128 v[234:237], v187
	ds_read_b128 v[238:241], v187 offset:32
	ds_read_b128 v[242:245], v187 offset:64
	ds_read_b128 v[252:255], v187 offset:96
	v_add_co_u32_e32 v246, vcc, 0xfff80000, v162
	global_load_dwordx4 v[140:143], v[166:167], off
	global_load_dwordx4 v[136:139], v[164:165], off
	v_addc_co_u32_e32 v247, vcc, -1, v163, vcc
	global_load_dwordx4 v[148:151], v[246:247], off
	global_load_dwordx4 v[144:147], v[162:163], off
	s_and_saveexec_b64 s[12:13], s[40:41]
	s_cbranch_execz .Lfx_nooffs_a
	global_load_dwordx4 v[132:135], v[160:161], off
	v_add_u32_e32 v250, s14, v185
	v_ashrrev_i32_e32 v250, 5, v250
	v_lshl_add_u32 v250, v250, 2, 0
	v_add_u32_e32 v250, 0x15200, v250
	ds_read_b32 v158, v250
.Lfx_nooffs_a:
	s_or_b64 exec, exec, s[12:13]
	s_waitcnt lgkmcnt(11)
	v_mfma_f32_32x32x16_bf16 v[84:99], v[84:87], v[128:131], 0
	v_add_u32_e32 v186, 31, v186
	v_cmp_gt_i32_e32 vcc, v186, v159
	s_waitcnt lgkmcnt(10)
	v_mfma_f32_32x32x16_bf16 v[84:99], v[188:191], v[124:127], v[84:99]
	s_waitcnt lgkmcnt(9)
	v_mfma_f32_32x32x16_bf16 v[84:99], v[208:211], v[120:123], v[84:99]
	s_waitcnt lgkmcnt(8)
	v_mfma_f32_32x32x16_bf16 v[84:99], v[212:215], v[112:115], v[84:99]
	s_waitcnt lgkmcnt(7)
	v_mfma_f32_32x32x16_bf16 v[84:99], v[216:219], v[116:119], v[84:99]
	s_waitcnt lgkmcnt(6)
	v_mfma_f32_32x32x16_bf16 v[84:99], v[220:223], v[108:111], v[84:99]
	s_waitcnt lgkmcnt(5)
	v_mfma_f32_32x32x16_bf16 v[84:99], v[224:227], v[104:107], v[84:99]
	s_waitcnt lgkmcnt(4)
	v_mfma_f32_32x32x16_bf16 v[84:99], v[228:231], v[100:103], v[84:99]
	s_waitcnt lgkmcnt(0)
	v_sub_f32_e32 v193, v1, v235
	v_sub_f32_e32 v192, v68, v234
	v_sub_f32_e32 v197, v77, v237
	v_sub_f32_e32 v196, v78, v236
	v_sub_f32_e32 v213, v75, v239
	v_sub_f32_e32 v212, v76, v238
	v_sub_f32_e32 v215, v73, v241
	v_sub_f32_e32 v214, v70, v240
	v_sub_f32_e32 v189, v69, v243
	v_sub_f32_e32 v188, v72, v242
	v_sub_f32_e32 v191, v71, v245
	v_sub_f32_e32 v190, v74, v244
	v_sub_f32_e32 v209, v79, v253
	v_sub_f32_e32 v208, v80, v252
	v_sub_f32_e32 v211, v81, v255
	v_sub_f32_e32 v210, v82, v254
	v_add_u32_e32 v246, s17, v170
	v_add_u32_e32 v247, 0xc800, v246
	v_add_u32_e32 v250, 0xd800, v246
	v_add_u32_e32 v251, 0xe800, v246
	v_add_u32_e32 v246, 0xf800, v246
	ds_read2_b64 v[234:237], v247 offset1:2
	ds_read2_b64 v[238:241], v247 offset0:4 offset1:6
	ds_read2_b64 v[242:245], v250 offset0:32 offset1:34
	ds_read2_b64 v[252:255], v250 offset0:36 offset1:38
	ds_read2_b64 v[224:227], v251 offset0:64 offset1:66
	ds_read2_b64 v[228:231], v251 offset0:68 offset1:70
	ds_read2_b64 v[216:219], v246 offset0:96 offset1:98
	ds_read2_b64 v[220:223], v246 offset0:100 offset1:102
	s_nop 1
	v_pk_fma_f32 v[98:99], v[98:99], s[24:25], v[210:211] op_sel_hi:[1,0,1]
	v_pk_fma_f32 v[96:97], v[96:97], s[24:25], v[208:209] op_sel_hi:[1,0,1]
	v_pk_fma_f32 v[94:95], v[94:95], s[24:25], v[190:191] op_sel_hi:[1,0,1]
	v_pk_fma_f32 v[92:93], v[92:93], s[24:25], v[188:189] op_sel_hi:[1,0,1]
	v_pk_fma_f32 v[90:91], v[90:91], s[24:25], v[214:215] op_sel_hi:[1,0,1]
	v_pk_fma_f32 v[88:89], v[88:89], s[24:25], v[212:213] op_sel_hi:[1,0,1]
	v_pk_fma_f32 v[86:87], v[86:87], s[24:25], v[196:197] op_sel_hi:[1,0,1]
	v_pk_fma_f32 v[84:85], v[84:85], s[24:25], v[192:193] op_sel_hi:[1,0,1]
	s_and_saveexec_b64 s[12:13], vcc
	s_cbranch_execz .LBB0_285
	v_add_u32_e32 v186, s14, v183
	v_cmp_lt_i32_e32 vcc, v186, v154
	v_add_u32_e32 v187, 2, v186
	s_nop 0
	v_cndmask_b32_e32 v85, v206, v85, vcc
	v_cmp_le_i32_e32 vcc, v186, v154
	s_nop 1
	v_cndmask_b32_e32 v84, v206, v84, vcc
	v_cmp_le_i32_e32 vcc, v187, v154
	v_add_u32_e32 v187, 3, v186
	s_nop 0
	v_cndmask_b32_e32 v86, v206, v86, vcc
	v_cmp_le_i32_e32 vcc, v187, v154
	v_add_u32_e32 v187, 8, v186
	s_nop 0
	v_cndmask_b32_e32 v87, v206, v87, vcc
	v_cmp_le_i32_e32 vcc, v187, v154
	v_add_u32_e32 v187, 9, v186
	s_nop 0
	v_cndmask_b32_e32 v88, v206, v88, vcc
	v_cmp_le_i32_e32 vcc, v187, v154
	v_add_u32_e32 v187, 10, v186
	s_nop 0
	v_cndmask_b32_e32 v89, v206, v89, vcc
	v_cmp_le_i32_e32 vcc, v187, v154
	v_add_u32_e32 v187, 11, v186
	s_nop 0
	v_cndmask_b32_e32 v90, v206, v90, vcc
	v_cmp_le_i32_e32 vcc, v187, v154
	v_add_u32_e32 v187, 16, v186
	s_nop 0
	v_cndmask_b32_e32 v91, v206, v91, vcc
	v_cmp_le_i32_e32 vcc, v187, v154
	v_add_u32_e32 v187, 17, v186
	s_nop 0
	v_cndmask_b32_e32 v92, v206, v92, vcc
	v_cmp_le_i32_e32 vcc, v187, v154
	v_add_u32_e32 v187, 18, v186
	s_nop 0
	v_cndmask_b32_e32 v93, v206, v93, vcc
	v_cmp_le_i32_e32 vcc, v187, v154
	v_add_u32_e32 v187, 19, v186
	s_nop 0
	v_cndmask_b32_e32 v94, v206, v94, vcc
	v_cmp_le_i32_e32 vcc, v187, v154
	v_add_u32_e32 v187, 24, v186
	s_nop 0
	v_cndmask_b32_e32 v95, v206, v95, vcc
	v_cmp_le_i32_e32 vcc, v187, v154
	v_add_u32_e32 v187, 25, v186
	s_nop 0
	v_cndmask_b32_e32 v96, v206, v96, vcc
	v_cmp_le_i32_e32 vcc, v187, v154
	v_add_u32_e32 v187, 26, v186
	v_add_u32_e32 v186, 27, v186
	v_cndmask_b32_e32 v97, v206, v97, vcc
	v_cmp_le_i32_e32 vcc, v187, v154
	s_nop 1
	v_cndmask_b32_e32 v98, v206, v98, vcc
	v_cmp_le_i32_e32 vcc, v186, v154
	s_nop 1
	v_cndmask_b32_e32 v99, v206, v99, vcc
